# v8 plus hand-written final norm (site 3): norm2 on all four norm sites
# baseline (speedup 1.0000x reference)
.LBB0_1276:
	v_readlane_b32 s2, v255, 0
	s_nop 0
	v_ashrrev_i32_e32 v0, 6, v147
	v_lshl_add_u32 v32, s2, 3, v0
	s_movk_i32 s2, 0x2000
	v_cmp_gt_i32_e32 vcc, s2, v32
	s_and_saveexec_b64 s[2:3], vcc
	s_cbranch_execz .LBB0_1279
	v_readlane_b32 s2, v255, 0
	v_readfirstlane_b32 s7, v147
	s_load_dwordx2 s[4:5], s[0:1], 0x90
	s_load_dwordx2 s[12:13], s[0:1], 0x98
	s_load_dwordx2 s[40:41], s[0:1], 0x48
	v_and_b32_e32 v0, 63, v147
	v_lshlrev_b32_e32 v1, 3, v0
	v_lshlrev_b32_e32 v0, 4, v0
	s_lshr_b32 s7, s7, 6
	s_lshl_b32 s2, s2, 3
	s_add_u32 s2, s2, s7
	s_lshl_b32 s24, s2, 2
	s_sub_u32 s27, s24, 0x1000
	s_lshr_b32 s27, s27, 10
	s_add_u32 s27, s27, 1
	s_cmp_lt_u32 s24, 0x1000
	s_cselect_b32 s30, 0, s27
	v_add_u32_e32 v2, 0x8000, v0
	v_mov_b32_e32 v3, v0
	v_add_u32_e32 v4, 0x1000, v0
	s_waitcnt lgkmcnt(0)
	s_lshl_b32 s27, s24, 11
	s_add_u32 s62, s12, s27
	s_addc_u32 s63, s13, 0
	s_add_u32 s58, s62, 0x8800000
	s_addc_u32 s59, s63, 0
	s_add_u32 s60, s58, 0x1000000
	s_addc_u32 s61, s59, 0
	s_add_u32 s62, s62, 0x1000000
	s_addc_u32 s63, s63, 0
	s_lshl_b32 s27, s24, 12
	s_add_u32 s46, s4, s27
	s_addc_u32 s47, s5, 0
	s_mov_b64 s[4:5], s[46:47]
	s_add_u32 s27, s30, 15
	s_mul_i32 s27, s27, 0x9000
	s_add_u32 s27, s27, 0x100000
	s_add_u32 s88, s12, s27
	s_addc_u32 s89, s13, 0
	s_mov_b64 s[100:101], s[88:89]
	s_mov_b32 s27, 0xb000
	s_add_u32 s40, s40, s27
	s_addc_u32 s41, s41, 0
	global_load_dwordx4 v[22:25], v2, s[100:101] offset:0
	global_load_dwordx4 v[38:41], v0, s[40:41] offset:0
	global_load_dwordx4 v[26:29], v2, s[100:101] offset:1024
	global_load_dwordx4 v[42:45], v0, s[40:41] offset:1024
	global_load_dwordx4 v[30:33], v2, s[100:101] offset:2048
	global_load_dwordx4 v[46:49], v0, s[40:41] offset:2048
	global_load_dwordx4 v[34:37], v2, s[100:101] offset:3072
	global_load_dwordx4 v[50:53], v0, s[40:41] offset:3072
	global_load_dwordx4 v[54:57], v0, s[4:5] offset:0
	global_load_dwordx4 v[58:61], v0, s[4:5] offset:1024
	global_load_dwordx4 v[62:65], v0, s[4:5] offset:2048
	global_load_dwordx4 v[66:69], v0, s[4:5] offset:3072
	global_load_dwordx2 v[70:71], v1, s[58:59] offset:0
	global_load_dwordx2 v[74:75], v1, s[58:59] offset:512
	global_load_dwordx2 v[78:79], v1, s[58:59] offset:1024
	global_load_dwordx2 v[82:83], v1, s[58:59] offset:1536
	global_load_dwordx2 v[72:73], v1, s[60:61] offset:0
	global_load_dwordx2 v[76:77], v1, s[60:61] offset:512
	global_load_dwordx2 v[80:81], v1, s[60:61] offset:1024
	global_load_dwordx2 v[84:85], v1, s[60:61] offset:1536
	s_add_u32 s4, s4, 0x1000
	s_addc_u32 s5, s5, 0
	s_add_u32 s58, s58, 0x800
	s_addc_u32 s59, s59, 0
	s_add_u32 s60, s60, 0x800
	s_addc_u32 s61, s61, 0
	global_load_dwordx4 v[86:89], v0, s[4:5] offset:0
	global_load_dwordx4 v[90:93], v0, s[4:5] offset:1024
	global_load_dwordx4 v[94:97], v0, s[4:5] offset:2048
	global_load_dwordx4 v[98:101], v0, s[4:5] offset:3072
	global_load_dwordx2 v[102:103], v1, s[58:59] offset:0
	global_load_dwordx2 v[106:107], v1, s[58:59] offset:512
	global_load_dwordx2 v[110:111], v1, s[58:59] offset:1024
	global_load_dwordx2 v[114:115], v1, s[58:59] offset:1536
	global_load_dwordx2 v[104:105], v1, s[60:61] offset:0
	global_load_dwordx2 v[108:109], v1, s[60:61] offset:512
	global_load_dwordx2 v[112:113], v1, s[60:61] offset:1024
	global_load_dwordx2 v[116:117], v1, s[60:61] offset:1536
	s_add_u32 s4, s4, 0x1000
	s_addc_u32 s5, s5, 0
	s_add_u32 s58, s58, 0x800
	s_addc_u32 s59, s59, 0
	s_add_u32 s60, s60, 0x800
	s_addc_u32 s61, s61, 0
	global_load_dwordx4 v[118:121], v0, s[4:5] offset:0
	global_load_dwordx4 v[122:125], v0, s[4:5] offset:1024
	global_load_dwordx4 v[134:137], v0, s[4:5] offset:2048
	global_load_dwordx4 v[138:141], v0, s[4:5] offset:3072
	global_load_dwordx2 v[154:155], v1, s[58:59] offset:0
	global_load_dwordx2 v[158:159], v1, s[58:59] offset:512
	global_load_dwordx2 v[162:163], v1, s[58:59] offset:1024
	global_load_dwordx2 v[168:169], v1, s[58:59] offset:1536
	global_load_dwordx2 v[156:157], v1, s[60:61] offset:0
	global_load_dwordx2 v[160:161], v1, s[60:61] offset:512
	global_load_dwordx2 v[164:165], v1, s[60:61] offset:1024
	global_load_dwordx2 v[170:171], v1, s[60:61] offset:1536
	s_add_u32 s4, s4, 0x1000
	s_addc_u32 s5, s5, 0
	s_add_u32 s58, s58, 0x800
	s_addc_u32 s59, s59, 0
	s_add_u32 s60, s60, 0x800
	s_addc_u32 s61, s61, 0
	s_waitcnt vmcnt(24)
	v_lshlrev_b32_e32 v14, 16, v70
	v_and_b32_e32 v15, 0xffff0000, v70
	v_lshlrev_b32_e32 v16, 16, v72
	v_and_b32_e32 v17, 0xffff0000, v72
	v_lshlrev_b32_e32 v18, 16, v71
	v_and_b32_e32 v19, 0xffff0000, v71
	v_lshlrev_b32_e32 v20, 16, v73
	v_and_b32_e32 v21, 0xffff0000, v73
	v_pk_add_f32 v[70:71], v[14:15], v[16:17]
	v_pk_add_f32 v[72:73], v[18:19], v[20:21]
	v_lshlrev_b32_e32 v14, 16, v74
	v_and_b32_e32 v15, 0xffff0000, v74
	v_lshlrev_b32_e32 v16, 16, v76
	v_and_b32_e32 v17, 0xffff0000, v76
	v_lshlrev_b32_e32 v18, 16, v75
	v_and_b32_e32 v19, 0xffff0000, v75
	v_lshlrev_b32_e32 v20, 16, v77
	v_and_b32_e32 v21, 0xffff0000, v77
	v_pk_add_f32 v[74:75], v[14:15], v[16:17]
	v_pk_add_f32 v[76:77], v[18:19], v[20:21]
	v_lshlrev_b32_e32 v14, 16, v78
	v_and_b32_e32 v15, 0xffff0000, v78
	v_lshlrev_b32_e32 v16, 16, v80
	v_and_b32_e32 v17, 0xffff0000, v80
	v_lshlrev_b32_e32 v18, 16, v79
	v_and_b32_e32 v19, 0xffff0000, v79
	v_lshlrev_b32_e32 v20, 16, v81
	v_and_b32_e32 v21, 0xffff0000, v81
	v_pk_add_f32 v[78:79], v[14:15], v[16:17]
	v_pk_add_f32 v[80:81], v[18:19], v[20:21]
	v_lshlrev_b32_e32 v14, 16, v82
	v_and_b32_e32 v15, 0xffff0000, v82
	v_lshlrev_b32_e32 v16, 16, v84
	v_and_b32_e32 v17, 0xffff0000, v84
	v_lshlrev_b32_e32 v18, 16, v83
	v_and_b32_e32 v19, 0xffff0000, v83
	v_lshlrev_b32_e32 v20, 16, v85
	v_and_b32_e32 v21, 0xffff0000, v85
	v_pk_add_f32 v[82:83], v[14:15], v[16:17]
	v_pk_add_f32 v[84:85], v[18:19], v[20:21]
	v_pk_mul_f32 v[12:13], v[70:71], v[70:71]
	v_pk_fma_f32 v[12:13], v[72:73], v[72:73], v[12:13]
	v_pk_fma_f32 v[12:13], v[74:75], v[74:75], v[12:13]
	v_pk_fma_f32 v[12:13], v[76:77], v[76:77], v[12:13]
	v_pk_fma_f32 v[12:13], v[78:79], v[78:79], v[12:13]
	v_pk_fma_f32 v[12:13], v[80:81], v[80:81], v[12:13]
	v_pk_fma_f32 v[12:13], v[82:83], v[82:83], v[12:13]
	v_pk_fma_f32 v[12:13], v[84:85], v[84:85], v[12:13]
	v_add_f32_e32 v5, v12, v13
	s_nop 1
	v_add_f32_dpp v5, v5, v5 quad_perm:[1,0,3,2] row_mask:0xf bank_mask:0xf
	s_nop 1
	v_add_f32_dpp v5, v5, v5 quad_perm:[2,3,0,1] row_mask:0xf bank_mask:0xf
	s_nop 1
	v_add_f32_dpp v5, v5, v5 row_half_mirror row_mask:0xf bank_mask:0xf
	s_nop 1
	v_add_f32_dpp v5, v5, v5 row_mirror row_mask:0xf bank_mask:0xf
	s_nop 1
	v_add_f32_dpp v5, v5, v5 row_bcast:15 row_mask:0xa bank_mask:0xf
	s_nop 1
	v_add_f32_dpp v5, v5, v5 row_bcast:31 row_mask:0xc bank_mask:0xf
	s_nop 1
	v_readlane_b32 s32, v5, 63
	s_nop 1
	v_mov_b32_e32 v6, s32
	v_fmamk_f32 v6, v6, 0x3a800000, v146
	v_rsq_f32_e32 v6, v6
	s_nop 0
	v_mul_f32_e32 v8, 0.5, v6
	v_pk_mul_f32 v[14:15], v[70:71], v[8:9] op_sel_hi:[1,0]
	v_pk_mul_f32 v[14:15], v[38:39], v[14:15]
	v_pk_fma_f32 v[54:55], v[22:23], v[14:15], v[54:55]
	v_pk_mul_f32 v[14:15], v[72:73], v[8:9] op_sel_hi:[1,0]
	v_pk_mul_f32 v[14:15], v[40:41], v[14:15]
	v_pk_fma_f32 v[56:57], v[24:25], v[14:15], v[56:57]
	v_pk_mul_f32 v[14:15], v[74:75], v[8:9] op_sel_hi:[1,0]
	v_pk_mul_f32 v[14:15], v[42:43], v[14:15]
	v_pk_fma_f32 v[58:59], v[26:27], v[14:15], v[58:59]
	v_pk_mul_f32 v[14:15], v[76:77], v[8:9] op_sel_hi:[1,0]
	v_pk_mul_f32 v[14:15], v[44:45], v[14:15]
	v_pk_fma_f32 v[60:61], v[28:29], v[14:15], v[60:61]
	v_pk_mul_f32 v[14:15], v[78:79], v[8:9] op_sel_hi:[1,0]
	v_pk_mul_f32 v[14:15], v[46:47], v[14:15]
	v_pk_fma_f32 v[62:63], v[30:31], v[14:15], v[62:63]
	v_pk_mul_f32 v[14:15], v[80:81], v[8:9] op_sel_hi:[1,0]
	v_pk_mul_f32 v[14:15], v[48:49], v[14:15]
	v_pk_fma_f32 v[64:65], v[32:33], v[14:15], v[64:65]
	v_pk_mul_f32 v[14:15], v[82:83], v[8:9] op_sel_hi:[1,0]
	v_pk_mul_f32 v[14:15], v[50:51], v[14:15]
	v_pk_fma_f32 v[66:67], v[34:35], v[14:15], v[66:67]
	v_pk_mul_f32 v[14:15], v[84:85], v[8:9] op_sel_hi:[1,0]
	v_pk_mul_f32 v[14:15], v[52:53], v[14:15]
	v_pk_fma_f32 v[68:69], v[36:37], v[14:15], v[68:69]
	global_store_dwordx4 v0, v[54:57], s[46:47] offset:0
	global_store_dwordx4 v0, v[58:61], s[46:47] offset:1024
	global_store_dwordx4 v0, v[62:65], s[46:47] offset:2048
	global_store_dwordx4 v0, v[66:69], s[46:47] offset:3072
	s_add_u32 s46, s46, 0x1000
	s_addc_u32 s47, s47, 0
	s_add_u32 s62, s62, 0x800
	s_addc_u32 s63, s63, 0
	s_nop 1
	global_load_dwordx4 v[54:57], v0, s[4:5] offset:0
	global_load_dwordx4 v[58:61], v0, s[4:5] offset:1024
	global_load_dwordx4 v[62:65], v0, s[4:5] offset:2048
	global_load_dwordx4 v[66:69], v0, s[4:5] offset:3072
	global_load_dwordx2 v[70:71], v1, s[58:59] offset:0
	global_load_dwordx2 v[74:75], v1, s[58:59] offset:512
	global_load_dwordx2 v[78:79], v1, s[58:59] offset:1024
	global_load_dwordx2 v[82:83], v1, s[58:59] offset:1536
	global_load_dwordx2 v[72:73], v1, s[60:61] offset:0
	global_load_dwordx2 v[76:77], v1, s[60:61] offset:512
	global_load_dwordx2 v[80:81], v1, s[60:61] offset:1024
	global_load_dwordx2 v[84:85], v1, s[60:61] offset:1536
	s_add_u32 s4, s4, 0x1000
	s_addc_u32 s5, s5, 0
	s_add_u32 s58, s58, 0x800
	s_addc_u32 s59, s59, 0
	s_add_u32 s60, s60, 0x800
	s_addc_u32 s61, s61, 0
	s_waitcnt vmcnt(28)
	v_lshlrev_b32_e32 v14, 16, v102
	v_and_b32_e32 v15, 0xffff0000, v102
	v_lshlrev_b32_e32 v16, 16, v104
	v_and_b32_e32 v17, 0xffff0000, v104
	v_lshlrev_b32_e32 v18, 16, v103
	v_and_b32_e32 v19, 0xffff0000, v103
	v_lshlrev_b32_e32 v20, 16, v105
	v_and_b32_e32 v21, 0xffff0000, v105
	v_pk_add_f32 v[102:103], v[14:15], v[16:17]
	v_pk_add_f32 v[104:105], v[18:19], v[20:21]
	v_lshlrev_b32_e32 v14, 16, v106
	v_and_b32_e32 v15, 0xffff0000, v106
	v_lshlrev_b32_e32 v16, 16, v108
	v_and_b32_e32 v17, 0xffff0000, v108
	v_lshlrev_b32_e32 v18, 16, v107
	v_and_b32_e32 v19, 0xffff0000, v107
	v_lshlrev_b32_e32 v20, 16, v109
	v_and_b32_e32 v21, 0xffff0000, v109
	v_pk_add_f32 v[106:107], v[14:15], v[16:17]
	v_pk_add_f32 v[108:109], v[18:19], v[20:21]
	v_lshlrev_b32_e32 v14, 16, v110
	v_and_b32_e32 v15, 0xffff0000, v110
	v_lshlrev_b32_e32 v16, 16, v112
	v_and_b32_e32 v17, 0xffff0000, v112
	v_lshlrev_b32_e32 v18, 16, v111
	v_and_b32_e32 v19, 0xffff0000, v111
	v_lshlrev_b32_e32 v20, 16, v113
	v_and_b32_e32 v21, 0xffff0000, v113
	v_pk_add_f32 v[110:111], v[14:15], v[16:17]
	v_pk_add_f32 v[112:113], v[18:19], v[20:21]
	v_lshlrev_b32_e32 v14, 16, v114
	v_and_b32_e32 v15, 0xffff0000, v114
	v_lshlrev_b32_e32 v16, 16, v116
	v_and_b32_e32 v17, 0xffff0000, v116
	v_lshlrev_b32_e32 v18, 16, v115
	v_and_b32_e32 v19, 0xffff0000, v115
	v_lshlrev_b32_e32 v20, 16, v117
	v_and_b32_e32 v21, 0xffff0000, v117
	v_pk_add_f32 v[114:115], v[14:15], v[16:17]
	v_pk_add_f32 v[116:117], v[18:19], v[20:21]
	v_pk_mul_f32 v[12:13], v[102:103], v[102:103]
	v_pk_fma_f32 v[12:13], v[104:105], v[104:105], v[12:13]
	v_pk_fma_f32 v[12:13], v[106:107], v[106:107], v[12:13]
	v_pk_fma_f32 v[12:13], v[108:109], v[108:109], v[12:13]
	v_pk_fma_f32 v[12:13], v[110:111], v[110:111], v[12:13]
	v_pk_fma_f32 v[12:13], v[112:113], v[112:113], v[12:13]
	v_pk_fma_f32 v[12:13], v[114:115], v[114:115], v[12:13]
	v_pk_fma_f32 v[12:13], v[116:117], v[116:117], v[12:13]
	v_add_f32_e32 v5, v12, v13
	s_nop 1
	v_add_f32_dpp v5, v5, v5 quad_perm:[1,0,3,2] row_mask:0xf bank_mask:0xf
	s_nop 1
	v_add_f32_dpp v5, v5, v5 quad_perm:[2,3,0,1] row_mask:0xf bank_mask:0xf
	s_nop 1
	v_add_f32_dpp v5, v5, v5 row_half_mirror row_mask:0xf bank_mask:0xf
	s_nop 1
	v_add_f32_dpp v5, v5, v5 row_mirror row_mask:0xf bank_mask:0xf
	s_nop 1
	v_add_f32_dpp v5, v5, v5 row_bcast:15 row_mask:0xa bank_mask:0xf
	s_nop 1
	v_add_f32_dpp v5, v5, v5 row_bcast:31 row_mask:0xc bank_mask:0xf
	s_nop 1
	v_readlane_b32 s32, v5, 63
	s_nop 1
	v_mov_b32_e32 v6, s32
	v_fmamk_f32 v6, v6, 0x3a800000, v146
	v_rsq_f32_e32 v6, v6
	s_nop 0
	v_mul_f32_e32 v8, 0.5, v6
	v_pk_mul_f32 v[14:15], v[102:103], v[8:9] op_sel_hi:[1,0]
	v_pk_mul_f32 v[14:15], v[38:39], v[14:15]
	v_pk_fma_f32 v[86:87], v[22:23], v[14:15], v[86:87]
	v_pk_mul_f32 v[14:15], v[104:105], v[8:9] op_sel_hi:[1,0]
	v_pk_mul_f32 v[14:15], v[40:41], v[14:15]
	v_pk_fma_f32 v[88:89], v[24:25], v[14:15], v[88:89]
	v_pk_mul_f32 v[14:15], v[106:107], v[8:9] op_sel_hi:[1,0]
	v_pk_mul_f32 v[14:15], v[42:43], v[14:15]
	v_pk_fma_f32 v[90:91], v[26:27], v[14:15], v[90:91]
	v_pk_mul_f32 v[14:15], v[108:109], v[8:9] op_sel_hi:[1,0]
	v_pk_mul_f32 v[14:15], v[44:45], v[14:15]
	v_pk_fma_f32 v[92:93], v[28:29], v[14:15], v[92:93]
	v_pk_mul_f32 v[14:15], v[110:111], v[8:9] op_sel_hi:[1,0]
	v_pk_mul_f32 v[14:15], v[46:47], v[14:15]
	v_pk_fma_f32 v[94:95], v[30:31], v[14:15], v[94:95]
	v_pk_mul_f32 v[14:15], v[112:113], v[8:9] op_sel_hi:[1,0]
	v_pk_mul_f32 v[14:15], v[48:49], v[14:15]
	v_pk_fma_f32 v[96:97], v[32:33], v[14:15], v[96:97]
	v_pk_mul_f32 v[14:15], v[114:115], v[8:9] op_sel_hi:[1,0]
	v_pk_mul_f32 v[14:15], v[50:51], v[14:15]
	v_pk_fma_f32 v[98:99], v[34:35], v[14:15], v[98:99]
	v_pk_mul_f32 v[14:15], v[116:117], v[8:9] op_sel_hi:[1,0]
	v_pk_mul_f32 v[14:15], v[52:53], v[14:15]
	v_pk_fma_f32 v[100:101], v[36:37], v[14:15], v[100:101]
	global_store_dwordx4 v0, v[86:89], s[46:47] offset:0
	global_store_dwordx4 v0, v[90:93], s[46:47] offset:1024
	global_store_dwordx4 v0, v[94:97], s[46:47] offset:2048
	global_store_dwordx4 v0, v[98:101], s[46:47] offset:3072
	s_add_u32 s46, s46, 0x1000
	s_addc_u32 s47, s47, 0
	s_add_u32 s62, s62, 0x800
	s_addc_u32 s63, s63, 0
	s_waitcnt vmcnt(20)
	v_lshlrev_b32_e32 v14, 16, v154
	v_and_b32_e32 v15, 0xffff0000, v154
	v_lshlrev_b32_e32 v16, 16, v156
	v_and_b32_e32 v17, 0xffff0000, v156
	v_lshlrev_b32_e32 v18, 16, v155
	v_and_b32_e32 v19, 0xffff0000, v155
	v_lshlrev_b32_e32 v20, 16, v157
	v_and_b32_e32 v21, 0xffff0000, v157
	v_pk_add_f32 v[154:155], v[14:15], v[16:17]
	v_pk_add_f32 v[156:157], v[18:19], v[20:21]
	v_lshlrev_b32_e32 v14, 16, v158
	v_and_b32_e32 v15, 0xffff0000, v158
	v_lshlrev_b32_e32 v16, 16, v160
	v_and_b32_e32 v17, 0xffff0000, v160
	v_lshlrev_b32_e32 v18, 16, v159
	v_and_b32_e32 v19, 0xffff0000, v159
	v_lshlrev_b32_e32 v20, 16, v161
	v_and_b32_e32 v21, 0xffff0000, v161
	v_pk_add_f32 v[158:159], v[14:15], v[16:17]
	v_pk_add_f32 v[160:161], v[18:19], v[20:21]
	v_lshlrev_b32_e32 v14, 16, v162
	v_and_b32_e32 v15, 0xffff0000, v162
	v_lshlrev_b32_e32 v16, 16, v164
	v_and_b32_e32 v17, 0xffff0000, v164
	v_lshlrev_b32_e32 v18, 16, v163
	v_and_b32_e32 v19, 0xffff0000, v163
	v_lshlrev_b32_e32 v20, 16, v165
	v_and_b32_e32 v21, 0xffff0000, v165
	v_pk_add_f32 v[162:163], v[14:15], v[16:17]
	v_pk_add_f32 v[164:165], v[18:19], v[20:21]
	v_lshlrev_b32_e32 v14, 16, v168
	v_and_b32_e32 v15, 0xffff0000, v168
	v_lshlrev_b32_e32 v16, 16, v170
	v_and_b32_e32 v17, 0xffff0000, v170
	v_lshlrev_b32_e32 v18, 16, v169
	v_and_b32_e32 v19, 0xffff0000, v169
	v_lshlrev_b32_e32 v20, 16, v171
	v_and_b32_e32 v21, 0xffff0000, v171
	v_pk_add_f32 v[168:169], v[14:15], v[16:17]
	v_pk_add_f32 v[170:171], v[18:19], v[20:21]
	v_pk_mul_f32 v[12:13], v[154:155], v[154:155]
	v_pk_fma_f32 v[12:13], v[156:157], v[156:157], v[12:13]
	v_pk_fma_f32 v[12:13], v[158:159], v[158:159], v[12:13]
	v_pk_fma_f32 v[12:13], v[160:161], v[160:161], v[12:13]
	v_pk_fma_f32 v[12:13], v[162:163], v[162:163], v[12:13]
	v_pk_fma_f32 v[12:13], v[164:165], v[164:165], v[12:13]
	v_pk_fma_f32 v[12:13], v[168:169], v[168:169], v[12:13]
	v_pk_fma_f32 v[12:13], v[170:171], v[170:171], v[12:13]
	v_add_f32_e32 v5, v12, v13
	s_nop 1
	v_add_f32_dpp v5, v5, v5 quad_perm:[1,0,3,2] row_mask:0xf bank_mask:0xf
	s_nop 1
	v_add_f32_dpp v5, v5, v5 quad_perm:[2,3,0,1] row_mask:0xf bank_mask:0xf
	s_nop 1
	v_add_f32_dpp v5, v5, v5 row_half_mirror row_mask:0xf bank_mask:0xf
	s_nop 1
	v_add_f32_dpp v5, v5, v5 row_mirror row_mask:0xf bank_mask:0xf
	s_nop 1
	v_add_f32_dpp v5, v5, v5 row_bcast:15 row_mask:0xa bank_mask:0xf
	s_nop 1
	v_add_f32_dpp v5, v5, v5 row_bcast:31 row_mask:0xc bank_mask:0xf
	s_nop 1
	v_readlane_b32 s32, v5, 63
	s_nop 1
	v_mov_b32_e32 v6, s32
	v_fmamk_f32 v6, v6, 0x3a800000, v146
	v_rsq_f32_e32 v6, v6
	s_nop 0
	v_mul_f32_e32 v8, 0.5, v6
	v_pk_mul_f32 v[14:15], v[154:155], v[8:9] op_sel_hi:[1,0]
	v_pk_mul_f32 v[14:15], v[38:39], v[14:15]
	v_pk_fma_f32 v[118:119], v[22:23], v[14:15], v[118:119]
	v_pk_mul_f32 v[14:15], v[156:157], v[8:9] op_sel_hi:[1,0]
	v_pk_mul_f32 v[14:15], v[40:41], v[14:15]
	v_pk_fma_f32 v[120:121], v[24:25], v[14:15], v[120:121]
	v_pk_mul_f32 v[14:15], v[158:159], v[8:9] op_sel_hi:[1,0]
	v_pk_mul_f32 v[14:15], v[42:43], v[14:15]
	v_pk_fma_f32 v[122:123], v[26:27], v[14:15], v[122:123]
	v_pk_mul_f32 v[14:15], v[160:161], v[8:9] op_sel_hi:[1,0]
	v_pk_mul_f32 v[14:15], v[44:45], v[14:15]
	v_pk_fma_f32 v[124:125], v[28:29], v[14:15], v[124:125]
	v_pk_mul_f32 v[14:15], v[162:163], v[8:9] op_sel_hi:[1,0]
	v_pk_mul_f32 v[14:15], v[46:47], v[14:15]
	v_pk_fma_f32 v[134:135], v[30:31], v[14:15], v[134:135]
	v_pk_mul_f32 v[14:15], v[164:165], v[8:9] op_sel_hi:[1,0]
	v_pk_mul_f32 v[14:15], v[48:49], v[14:15]
	v_pk_fma_f32 v[136:137], v[32:33], v[14:15], v[136:137]
	v_pk_mul_f32 v[14:15], v[168:169], v[8:9] op_sel_hi:[1,0]
	v_pk_mul_f32 v[14:15], v[50:51], v[14:15]
	v_pk_fma_f32 v[138:139], v[34:35], v[14:15], v[138:139]
	v_pk_mul_f32 v[14:15], v[170:171], v[8:9] op_sel_hi:[1,0]
	v_pk_mul_f32 v[14:15], v[52:53], v[14:15]
	v_pk_fma_f32 v[140:141], v[36:37], v[14:15], v[140:141]
	global_store_dwordx4 v0, v[118:121], s[46:47] offset:0
	global_store_dwordx4 v0, v[122:125], s[46:47] offset:1024
	global_store_dwordx4 v0, v[134:137], s[46:47] offset:2048
	global_store_dwordx4 v0, v[138:141], s[46:47] offset:3072
	s_add_u32 s46, s46, 0x1000
	s_addc_u32 s47, s47, 0
	s_add_u32 s62, s62, 0x800
	s_addc_u32 s63, s63, 0
	s_waitcnt vmcnt(8)
	v_lshlrev_b32_e32 v14, 16, v70
	v_and_b32_e32 v15, 0xffff0000, v70
	v_lshlrev_b32_e32 v16, 16, v72
	v_and_b32_e32 v17, 0xffff0000, v72
	v_lshlrev_b32_e32 v18, 16, v71
	v_and_b32_e32 v19, 0xffff0000, v71
	v_lshlrev_b32_e32 v20, 16, v73
	v_and_b32_e32 v21, 0xffff0000, v73
	v_pk_add_f32 v[70:71], v[14:15], v[16:17]
	v_pk_add_f32 v[72:73], v[18:19], v[20:21]
	v_lshlrev_b32_e32 v14, 16, v74
	v_and_b32_e32 v15, 0xffff0000, v74
	v_lshlrev_b32_e32 v16, 16, v76
	v_and_b32_e32 v17, 0xffff0000, v76
	v_lshlrev_b32_e32 v18, 16, v75
	v_and_b32_e32 v19, 0xffff0000, v75
	v_lshlrev_b32_e32 v20, 16, v77
	v_and_b32_e32 v21, 0xffff0000, v77
	v_pk_add_f32 v[74:75], v[14:15], v[16:17]
	v_pk_add_f32 v[76:77], v[18:19], v[20:21]
	v_lshlrev_b32_e32 v14, 16, v78
	v_and_b32_e32 v15, 0xffff0000, v78
	v_lshlrev_b32_e32 v16, 16, v80
	v_and_b32_e32 v17, 0xffff0000, v80
	v_lshlrev_b32_e32 v18, 16, v79
	v_and_b32_e32 v19, 0xffff0000, v79
	v_lshlrev_b32_e32 v20, 16, v81
	v_and_b32_e32 v21, 0xffff0000, v81
	v_pk_add_f32 v[78:79], v[14:15], v[16:17]
	v_pk_add_f32 v[80:81], v[18:19], v[20:21]
	v_lshlrev_b32_e32 v14, 16, v82
	v_and_b32_e32 v15, 0xffff0000, v82
	v_lshlrev_b32_e32 v16, 16, v84
	v_and_b32_e32 v17, 0xffff0000, v84
	v_lshlrev_b32_e32 v18, 16, v83
	v_and_b32_e32 v19, 0xffff0000, v83
	v_lshlrev_b32_e32 v20, 16, v85
	v_and_b32_e32 v21, 0xffff0000, v85
	v_pk_add_f32 v[82:83], v[14:15], v[16:17]
	v_pk_add_f32 v[84:85], v[18:19], v[20:21]
	v_pk_mul_f32 v[12:13], v[70:71], v[70:71]
	v_pk_fma_f32 v[12:13], v[72:73], v[72:73], v[12:13]
	v_pk_fma_f32 v[12:13], v[74:75], v[74:75], v[12:13]
	v_pk_fma_f32 v[12:13], v[76:77], v[76:77], v[12:13]
	v_pk_fma_f32 v[12:13], v[78:79], v[78:79], v[12:13]
	v_pk_fma_f32 v[12:13], v[80:81], v[80:81], v[12:13]
	v_pk_fma_f32 v[12:13], v[82:83], v[82:83], v[12:13]
	v_pk_fma_f32 v[12:13], v[84:85], v[84:85], v[12:13]
	v_add_f32_e32 v5, v12, v13
	s_nop 1
	v_add_f32_dpp v5, v5, v5 quad_perm:[1,0,3,2] row_mask:0xf bank_mask:0xf
	s_nop 1
	v_add_f32_dpp v5, v5, v5 quad_perm:[2,3,0,1] row_mask:0xf bank_mask:0xf
	s_nop 1
	v_add_f32_dpp v5, v5, v5 row_half_mirror row_mask:0xf bank_mask:0xf
	s_nop 1
	v_add_f32_dpp v5, v5, v5 row_mirror row_mask:0xf bank_mask:0xf
	s_nop 1
	v_add_f32_dpp v5, v5, v5 row_bcast:15 row_mask:0xa bank_mask:0xf
	s_nop 1
	v_add_f32_dpp v5, v5, v5 row_bcast:31 row_mask:0xc bank_mask:0xf
	s_nop 1
	v_readlane_b32 s32, v5, 63
	s_nop 1
	v_mov_b32_e32 v6, s32
	v_fmamk_f32 v6, v6, 0x3a800000, v146
	v_rsq_f32_e32 v6, v6
	s_nop 0
	v_mul_f32_e32 v8, 0.5, v6
	v_pk_mul_f32 v[14:15], v[70:71], v[8:9] op_sel_hi:[1,0]
	v_pk_mul_f32 v[14:15], v[38:39], v[14:15]
	v_pk_fma_f32 v[54:55], v[22:23], v[14:15], v[54:55]
	v_pk_mul_f32 v[14:15], v[72:73], v[8:9] op_sel_hi:[1,0]
	v_pk_mul_f32 v[14:15], v[40:41], v[14:15]
	v_pk_fma_f32 v[56:57], v[24:25], v[14:15], v[56:57]
	v_pk_mul_f32 v[14:15], v[74:75], v[8:9] op_sel_hi:[1,0]
	v_pk_mul_f32 v[14:15], v[42:43], v[14:15]
	v_pk_fma_f32 v[58:59], v[26:27], v[14:15], v[58:59]
	v_pk_mul_f32 v[14:15], v[76:77], v[8:9] op_sel_hi:[1,0]
	v_pk_mul_f32 v[14:15], v[44:45], v[14:15]
	v_pk_fma_f32 v[60:61], v[28:29], v[14:15], v[60:61]
	v_pk_mul_f32 v[14:15], v[78:79], v[8:9] op_sel_hi:[1,0]
	v_pk_mul_f32 v[14:15], v[46:47], v[14:15]
	v_pk_fma_f32 v[62:63], v[30:31], v[14:15], v[62:63]
	v_pk_mul_f32 v[14:15], v[80:81], v[8:9] op_sel_hi:[1,0]
	v_pk_mul_f32 v[14:15], v[48:49], v[14:15]
	v_pk_fma_f32 v[64:65], v[32:33], v[14:15], v[64:65]
	v_pk_mul_f32 v[14:15], v[82:83], v[8:9] op_sel_hi:[1,0]
	v_pk_mul_f32 v[14:15], v[50:51], v[14:15]
	v_pk_fma_f32 v[66:67], v[34:35], v[14:15], v[66:67]
	v_pk_mul_f32 v[14:15], v[84:85], v[8:9] op_sel_hi:[1,0]
	v_pk_mul_f32 v[14:15], v[52:53], v[14:15]
	v_pk_fma_f32 v[68:69], v[36:37], v[14:15], v[68:69]
	global_store_dwordx4 v0, v[54:57], s[46:47] offset:0
	global_store_dwordx4 v0, v[58:61], s[46:47] offset:1024
	global_store_dwordx4 v0, v[62:65], s[46:47] offset:2048
	global_store_dwordx4 v0, v[66:69], s[46:47] offset:3072
	s_add_u32 s46, s46, 0x1000
	s_addc_u32 s47, s47, 0
	s_add_u32 s62, s62, 0x800
	s_addc_u32 s63, s63, 0
